# P1 tail round also 4 K-slices of 512 instead of 8 of 256 (on top of the P5 change)
# baseline (speedup 1.0000x reference)
.LBB0_298:
	s_cmp_eq_u32 s40, 0
	s_cbranch_scc1 .LBB0_405
	s_add_u32 s6, s96, 0x14ec0000
	s_addc_u32 s7, s97, 0
	s_lshl_b32 s9, s40, 3
	s_cmp_lt_i32 s88, s9
	s_cselect_b64 s[16:17], -1, 0
	s_lshl_b32 s100, s40, 2
	s_cmp_ge_i32 s88, s100
	v_readfirstlane_b32 s22, v208
	v_readlane_b32 s76, v245, 54
	v_readlane_b32 s77, v245, 55
	v_readlane_b32 s78, v245, 56
	v_readlane_b32 s79, v245, 57
	s_cbranch_scc1 .LBB0_328
	s_ashr_i32 s2, s88, 31
	s_lshr_b32 s2, s2, 30
	s_add_i32 s2, s88, s2
	s_ashr_i32 s3, s2, 2
	s_add_i32 s2, s8, s3
	s_ashr_i32 s4, s2, 31
	s_lshr_b32 s4, s4, 29
	s_add_i32 s19, s2, s4
	s_and_b32 s4, s19, -8
	s_sub_i32 s2, s2, s4
	s_mov_b64 s[80:81], s[96:97]
	s_cmp_gt_i32 s2, 1
	s_cbranch_scc0 .LBB0_302
	s_mul_i32 s4, s2, 0x83
	s_add_i32 s18, s4, 2
	s_mov_b64 s[4:5], 0
	s_branch .LBB0_303

.LBB0_305:
	s_add_i32 s18, s18, s4
	s_mul_hi_i32 s2, s18, 0x88888889
	s_add_i32 s2, s2, s18
	s_lshr_b32 s4, s2, 31
	s_ashr_i32 s2, s2, 6
	s_add_i32 s19, s2, s4
	s_lshl_b32 s20, s19, 2
	s_sub_i32 s2, 35, s20
	s_min_i32 s21, s2, 4
	s_abs_i32 s23, s21
	v_cvt_f32_u32_e32 v0, s23
	s_sub_i32 s25, 0, s23
	s_mulk_i32 s19, 0x78
	s_sub_i32 s19, s18, s19
	v_rcp_iflag_f32_e32 v0, v0
	s_abs_i32 s24, s19
	s_lshr_b32 s4, s22, 6
	s_xor_b32 s18, s19, s21
	v_mul_f32_e32 v0, 0x4f7ffffe, v0
	v_cvt_u32_f32_e32 v0, v0
	s_lshr_b32 s5, s22, 8
	s_lshl_b32 s2, s4, 10
	s_ashr_i32 s18, s18, 31
	v_readfirstlane_b32 s26, v0
	s_mul_i32 s25, s25, s26
	s_mul_hi_u32 s25, s26, s25
	s_add_i32 s26, s26, s25
	s_mul_hi_u32 s25, s24, s26
	s_mul_i32 s26, s25, s23
	s_sub_i32 s24, s24, s26
	s_add_i32 s26, s25, 1
	s_sub_i32 s27, s24, s23
	s_cmp_ge_u32 s24, s23
	s_cselect_b32 s25, s26, s25
	s_cselect_b32 s24, s27, s24
	s_add_i32 s26, s25, 1
	s_cmp_ge_u32 s24, s23
	s_cselect_b32 s23, s26, s25
	s_xor_b32 s23, s23, s18
	s_sub_i32 s18, s23, s18
	s_mul_i32 s21, s18, s21
	s_sub_i32 s19, s19, s21
	s_lshl_b32 s3, s3, 2
	s_add_i32 s20, s20, s19
	s_sub_i32 s24, s88, s3
	s_ashr_i32 s21, s20, 31
	s_ashr_i32 s25, s24, 31
	s_ashr_i32 s19, s18, 31
	s_lshl_b64 s[20:21], s[20:21], 20
	s_lshl_b64 s[26:27], s[24:25], 10
	s_lshl_b64 s[18:19], s[18:19], 20
	s_add_u32 s3, s58, s18
	s_addc_u32 s18, s59, s19
	s_add_u32 s24, s3, s26
	s_addc_u32 s25, s18, s27
	s_add_i32 s3, s2, 0
	s_add_i32 m0, s3, 0x10000
	v_mov_b32_e32 v133, 0
	global_load_lds_dwordx4 v132, s[24:25]
	s_add_i32 m0, s3, 0x12000
	s_add_u32 s20, s56, s20
	s_addc_u32 s21, s57, s21
	s_add_u32 s18, s24, 0x80000
	global_load_lds_dwordx4 v136, s[24:25]
	s_addc_u32 s19, s25, 0
	s_add_i32 m0, s3, 0x14000
	v_mov_b32_e32 v137, v133
	global_load_lds_dwordx4 v132, s[18:19]
	s_add_i32 m0, s3, 0x16000
	s_add_u32 s34, s20, s26
	s_addc_u32 s35, s21, s27
	s_add_i32 s60, s3, 0x2000
	global_load_lds_dwordx4 v136, s[18:19]
	s_mov_b32 m0, s3
	s_add_u32 s18, s34, 0x80000
	global_load_lds_dwordx4 v130, s[34:35]
	s_mov_b32 m0, s60
	s_addc_u32 s19, s35, 0
	s_add_i32 s61, s3, 0x4000
	global_load_lds_dwordx4 v134, s[34:35]
	s_mov_b32 m0, s61
	s_add_i32 s62, s3, 0x6000
	global_load_lds_dwordx4 v130, s[18:19]
	s_mov_b32 m0, s62
	v_mov_b32_e32 v131, v133
	global_load_lds_dwordx4 v134, s[18:19]
	v_mov_b32_e32 v135, v133
	s_cmp_eq_u32 s5, 1
	s_mov_b32 s63, 0
	v_lshl_add_u64 v[6:7], s[24:25], 0, v[132:133]
	v_lshl_add_u64 v[4:5], s[24:25], 0, v[136:137]
	v_lshl_add_u64 v[0:1], s[34:35], 0, v[130:131]
	s_cselect_b64 s[18:19], -1, 0
	s_cmp_lg_u32 s5, 1
	v_lshl_add_u64 v[2:3], s[34:35], 0, v[134:135]
	s_cbranch_scc1 .LBB0_307
	s_barrier

.LBB0_320:
	v_mov_b32_e32 v0, 0
	s_mov_b32 s27, 0
	s_mov_b32 s101, 0
	s_mov_b64 s[42:43], -1
	s_mov_b64 s[44:45], 0
	v_mov_b32_e32 v1, v0
	v_mov_b32_e32 v2, v0
	v_mov_b32_e32 v3, v0
	v_mov_b32_e32 v4, v0
	v_mov_b32_e32 v5, v0
	v_mov_b32_e32 v6, v0
	v_mov_b32_e32 v7, v0
	v_mov_b32_e32 v8, v0
	v_mov_b32_e32 v9, v0
	v_mov_b32_e32 v10, v0
	v_mov_b32_e32 v11, v0
	v_mov_b32_e32 v12, v0
	v_mov_b32_e32 v13, v0
	v_mov_b32_e32 v14, v0
	v_mov_b32_e32 v15, v0
	v_mov_b32_e32 v16, v0
	v_mov_b32_e32 v17, v0
	v_mov_b32_e32 v18, v0
	v_mov_b32_e32 v19, v0
	v_mov_b32_e32 v20, v0
	v_mov_b32_e32 v21, v0
	v_mov_b32_e32 v22, v0
	v_mov_b32_e32 v23, v0
	v_mov_b32_e32 v24, v0
	v_mov_b32_e32 v25, v0
	v_mov_b32_e32 v26, v0
	v_mov_b32_e32 v27, v0
	v_mov_b32_e32 v28, v0
	v_mov_b32_e32 v29, v0
	v_mov_b32_e32 v30, v0
	v_mov_b32_e32 v31, v0
	v_mov_b32_e32 v32, v0
	v_mov_b32_e32 v33, v0
	v_mov_b32_e32 v34, v0
	v_mov_b32_e32 v35, v0
	v_mov_b32_e32 v36, v0
	v_mov_b32_e32 v37, v0
	v_mov_b32_e32 v38, v0
	v_mov_b32_e32 v39, v0
	v_mov_b32_e32 v40, v0
	v_mov_b32_e32 v41, v0
	v_mov_b32_e32 v42, v0
	v_mov_b32_e32 v43, v0
	v_mov_b32_e32 v44, v0
	v_mov_b32_e32 v45, v0
	v_mov_b32_e32 v46, v0
	v_mov_b32_e32 v47, v0
	v_mov_b32_e32 v48, v0
	v_mov_b32_e32 v49, v0
	v_mov_b32_e32 v50, v0
	v_mov_b32_e32 v51, v0
	v_mov_b32_e32 v52, v0
	v_mov_b32_e32 v53, v0
	v_mov_b32_e32 v54, v0
	v_mov_b32_e32 v55, v0
	v_mov_b32_e32 v56, v0
	v_mov_b32_e32 v57, v0
	v_mov_b32_e32 v58, v0
	v_mov_b32_e32 v59, v0
	v_mov_b32_e32 v60, v0
	v_mov_b32_e32 v61, v0
	v_mov_b32_e32 v62, v0
	v_mov_b32_e32 v63, v0
	v_mov_b32_e32 v64, v0
	v_mov_b32_e32 v65, v0
	v_mov_b32_e32 v66, v0
	v_mov_b32_e32 v67, v0
	v_mov_b32_e32 v68, v0
	v_mov_b32_e32 v69, v0
	v_mov_b32_e32 v70, v0
	v_mov_b32_e32 v71, v0
	v_mov_b32_e32 v72, v0
	v_mov_b32_e32 v73, v0
	v_mov_b32_e32 v74, v0
	v_mov_b32_e32 v75, v0
	v_mov_b32_e32 v76, v0
	v_mov_b32_e32 v77, v0
	v_mov_b32_e32 v78, v0
	v_mov_b32_e32 v79, v0
	v_mov_b32_e32 v80, v0
	v_mov_b32_e32 v81, v0
	v_mov_b32_e32 v82, v0
	v_mov_b32_e32 v83, v0
	v_mov_b32_e32 v84, v0
	v_mov_b32_e32 v85, v0
	v_mov_b32_e32 v86, v0
	v_mov_b32_e32 v87, v0
	v_mov_b32_e32 v88, v0
	v_mov_b32_e32 v89, v0
	v_mov_b32_e32 v90, v0
	v_mov_b32_e32 v91, v0
	v_mov_b32_e32 v92, v0
	v_mov_b32_e32 v93, v0
	v_mov_b32_e32 v94, v0
	v_mov_b32_e32 v95, v0
	v_mov_b32_e32 v96, v0
	v_mov_b32_e32 v97, v0
	v_mov_b32_e32 v98, v0
	v_mov_b32_e32 v99, v0
	v_mov_b32_e32 v100, v0
	v_mov_b32_e32 v101, v0
	v_mov_b32_e32 v102, v0
	v_mov_b32_e32 v103, v0
	v_mov_b32_e32 v104, v0
	v_mov_b32_e32 v105, v0
	v_mov_b32_e32 v106, v0
	v_mov_b32_e32 v107, v0
	v_mov_b32_e32 v108, v0
	v_mov_b32_e32 v109, v0
	v_mov_b32_e32 v110, v0
	v_mov_b32_e32 v111, v0
	v_mov_b32_e32 v112, v0
	v_mov_b32_e32 v113, v0
	v_mov_b32_e32 v114, v0
	v_mov_b32_e32 v115, v0
	v_mov_b32_e32 v116, v0
	v_mov_b32_e32 v117, v0
	v_mov_b32_e32 v118, v0
	v_mov_b32_e32 v119, v0
	v_mov_b32_e32 v120, v0
	v_mov_b32_e32 v121, v0
	v_mov_b32_e32 v122, v0
	v_mov_b32_e32 v123, v0
	v_mov_b32_e32 v124, v0
	v_mov_b32_e32 v125, v0
	v_mov_b32_e32 v126, v0
	v_mov_b32_e32 v127, v0
.LBB0_321:
	s_add_u32 s29, s34, s27
	s_addc_u32 s31, s35, 0
	s_add_u32 s41, s29, 0x100
	s_addc_u32 s48, s31, 0
	s_and_b64 s[46:47], s[44:45], exec
	s_cselect_b32 s49, s37, s48
	s_cselect_b32 s48, s36, s41
	s_add_u32 s27, s24, s27
	s_addc_u32 s41, s25, 0
	s_add_u32 s27, s27, 0x100
	s_addc_u32 s41, s41, 0
	s_and_b64 s[44:45], s[44:45], exec
	s_cselect_b32 s51, s39, s41
	s_cselect_b32 s50, s38, s27
	s_add_u32 s54, s29, 0x80080
	s_addc_u32 s55, s31, 0
	s_add_i32 s74, s66, s2
	ds_read_b128 v[144:147], v129
	ds_read_b128 v[148:151], v129 offset:1024
	ds_read_b128 v[152:155], v129 offset:2048
	ds_read_b128 v[156:159], v129 offset:3072
	ds_read_b128 v[164:167], v141
	ds_read_b128 v[168:171], v141 offset:1024
	ds_read_b128 v[172:175], v141 offset:2048
	ds_read_b128 v[180:183], v141 offset:3072
	s_add_i32 m0, s3, 0xc000
	s_add_i32 s75, s3, 0xe000
	s_add_i32 s71, s74, 0x2000
	s_add_u32 s52, s50, 0x80000
	s_addc_u32 s53, s51, 0
	s_add_i32 s73, s67, s2
	s_add_i32 s72, s73, 0x2000
	s_add_i32 s70, 0, 0x18000
	s_add_i32 s69, 0, 0x1c000
	s_add_u32 s46, s48, 0x80000
	s_addc_u32 s47, s49, 0
	s_add_i32 s41, s70, s2
	s_add_i32 s29, s41, 0x2000
	s_add_u32 s44, s50, 0x80080
	s_addc_u32 s45, s51, 0
	s_add_i32 s31, s69, s2
	s_add_i32 s27, s31, 0x2000
	v_lshl_add_u64 v[160:161], s[54:55], 0, v[130:131]
	ds_read_b128 v[184:187], v142
	ds_read_b128 v[188:191], v142 offset:1024
	ds_read_b128 v[192:195], v142 offset:2048
	ds_read_b128 v[196:199], v142 offset:3072
	ds_read_b128 v[200:203], v142 offset:4096
	ds_read_b128 v[204:207], v142 offset:5120
	ds_read_b128 v[210:213], v142 offset:6144
	ds_read_b128 v[214:217], v142 offset:7168
	global_load_lds_dwordx4 v[160:161], off
	v_lshl_add_u64 v[160:161], s[54:55], 0, v[134:135]
	s_mov_b32 m0, s75
	s_nop 0
	global_load_lds_dwordx4 v[160:161], off
	s_waitcnt vmcnt(8)
	s_waitcnt lgkmcnt(0)
	s_barrier
	s_setprio 1
	s_waitcnt lgkmcnt(0)
	v_mfma_f32_16x16x32_bf16 v[124:127], v[144:147], v[184:187], v[124:127]
	v_mfma_f32_16x16x32_bf16 v[120:123], v[152:155], v[184:187], v[120:123]
	v_mfma_f32_16x16x32_bf16 v[116:119], v[144:147], v[192:195], v[116:119]
	v_mfma_f32_16x16x32_bf16 v[112:115], v[152:155], v[192:195], v[112:115]
	v_mfma_f32_16x16x32_bf16 v[108:111], v[144:147], v[200:203], v[108:111]
	v_mfma_f32_16x16x32_bf16 v[104:107], v[152:155], v[200:203], v[104:107]
	v_mfma_f32_16x16x32_bf16 v[100:103], v[144:147], v[210:213], v[100:103]
	v_mfma_f32_16x16x32_bf16 v[96:99], v[152:155], v[210:213], v[96:99]
	v_mfma_f32_16x16x32_bf16 v[124:127], v[148:151], v[188:191], v[124:127]
	v_mfma_f32_16x16x32_bf16 v[120:123], v[156:159], v[188:191], v[120:123]
	v_mfma_f32_16x16x32_bf16 v[116:119], v[148:151], v[196:199], v[116:119]
	v_mfma_f32_16x16x32_bf16 v[112:115], v[156:159], v[196:199], v[112:115]
	v_mfma_f32_16x16x32_bf16 v[108:111], v[148:151], v[204:207], v[108:111]
	v_mfma_f32_16x16x32_bf16 v[104:107], v[156:159], v[204:207], v[104:107]
	v_mfma_f32_16x16x32_bf16 v[100:103], v[148:151], v[214:217], v[100:103]
	v_mfma_f32_16x16x32_bf16 v[96:99], v[156:159], v[214:217], v[96:99]
	v_mfma_f32_16x16x32_bf16 v[92:95], v[164:167], v[184:187], v[92:95]
	v_mfma_f32_16x16x32_bf16 v[88:91], v[172:175], v[184:187], v[88:91]
	v_mfma_f32_16x16x32_bf16 v[84:87], v[164:167], v[192:195], v[84:87]
	v_mfma_f32_16x16x32_bf16 v[80:83], v[172:175], v[192:195], v[80:83]
	v_mfma_f32_16x16x32_bf16 v[76:79], v[164:167], v[200:203], v[76:79]
	v_mfma_f32_16x16x32_bf16 v[72:75], v[172:175], v[200:203], v[72:75]
	v_mfma_f32_16x16x32_bf16 v[68:71], v[164:167], v[210:213], v[68:71]
	v_mfma_f32_16x16x32_bf16 v[64:67], v[172:175], v[210:213], v[64:67]
	v_mfma_f32_16x16x32_bf16 v[92:95], v[168:171], v[188:191], v[92:95]
	v_mfma_f32_16x16x32_bf16 v[88:91], v[180:183], v[188:191], v[88:91]
	v_mfma_f32_16x16x32_bf16 v[84:87], v[168:171], v[196:199], v[84:87]
	v_mfma_f32_16x16x32_bf16 v[80:83], v[180:183], v[196:199], v[80:83]
	v_mfma_f32_16x16x32_bf16 v[76:79], v[168:171], v[204:207], v[76:79]
	v_mfma_f32_16x16x32_bf16 v[72:75], v[180:183], v[204:207], v[72:75]
	v_mfma_f32_16x16x32_bf16 v[68:71], v[168:171], v[214:217], v[68:71]
	v_mfma_f32_16x16x32_bf16 v[64:67], v[180:183], v[214:217], v[64:67]
	s_setprio 0
	s_barrier
	s_mov_b32 m0, s74
	v_lshl_add_u64 v[160:161], s[50:51], 0, v[132:133]
	ds_read_b128 v[184:187], v142 offset:16384
	ds_read_b128 v[188:191], v142 offset:17408
	ds_read_b128 v[192:195], v142 offset:18432
	ds_read_b128 v[196:199], v142 offset:19456
	ds_read_b128 v[200:203], v142 offset:20480
	ds_read_b128 v[204:207], v142 offset:21504
	ds_read_b128 v[210:213], v142 offset:22528
	ds_read_b128 v[214:217], v142 offset:23552
	global_load_lds_dwordx4 v[160:161], off
	v_lshl_add_u64 v[176:177], s[50:51], 0, v[136:137]
	s_mov_b32 m0, s71
	v_lshl_add_u64 v[218:219], s[52:53], 0, v[132:133]
	global_load_lds_dwordx4 v[176:177], off
	s_mov_b32 m0, s73
	v_lshl_add_u64 v[220:221], s[48:49], 0, v[134:135]
	global_load_lds_dwordx4 v[218:219], off
	v_lshl_add_u64 v[218:219], s[52:53], 0, v[136:137]
	s_mov_b32 m0, s72
	s_nop 0
	global_load_lds_dwordx4 v[218:219], off
	v_lshl_add_u64 v[218:219], s[48:49], 0, v[130:131]
	s_mov_b32 m0, s3
	s_nop 0
	global_load_lds_dwordx4 v[218:219], off
	s_mov_b32 m0, s60
	s_nop 0
	global_load_lds_dwordx4 v[220:221], off
	s_waitcnt vmcnt(8)
	s_waitcnt lgkmcnt(0)
	s_barrier
	s_setprio 1
	s_waitcnt lgkmcnt(0)
	v_mfma_f32_16x16x32_bf16 v[60:63], v[144:147], v[184:187], v[60:63]
	v_mfma_f32_16x16x32_bf16 v[56:59], v[152:155], v[184:187], v[56:59]
	v_mfma_f32_16x16x32_bf16 v[52:55], v[144:147], v[192:195], v[52:55]
	v_mfma_f32_16x16x32_bf16 v[48:51], v[152:155], v[192:195], v[48:51]
	v_mfma_f32_16x16x32_bf16 v[44:47], v[144:147], v[200:203], v[44:47]
	v_mfma_f32_16x16x32_bf16 v[40:43], v[152:155], v[200:203], v[40:43]
	v_mfma_f32_16x16x32_bf16 v[36:39], v[144:147], v[210:213], v[36:39]
	v_mfma_f32_16x16x32_bf16 v[32:35], v[152:155], v[210:213], v[32:35]
	v_mfma_f32_16x16x32_bf16 v[60:63], v[148:151], v[188:191], v[60:63]
	v_mfma_f32_16x16x32_bf16 v[56:59], v[156:159], v[188:191], v[56:59]
	v_mfma_f32_16x16x32_bf16 v[52:55], v[148:151], v[196:199], v[52:55]
	v_mfma_f32_16x16x32_bf16 v[48:51], v[156:159], v[196:199], v[48:51]
	v_mfma_f32_16x16x32_bf16 v[44:47], v[148:151], v[204:207], v[44:47]
	v_mfma_f32_16x16x32_bf16 v[40:43], v[156:159], v[204:207], v[40:43]
	v_mfma_f32_16x16x32_bf16 v[36:39], v[148:151], v[214:217], v[36:39]
	v_mfma_f32_16x16x32_bf16 v[32:35], v[156:159], v[214:217], v[32:35]
	v_mfma_f32_16x16x32_bf16 v[28:31], v[164:167], v[184:187], v[28:31]
	v_mfma_f32_16x16x32_bf16 v[24:27], v[172:175], v[184:187], v[24:27]
	v_mfma_f32_16x16x32_bf16 v[20:23], v[164:167], v[192:195], v[20:23]
	v_mfma_f32_16x16x32_bf16 v[16:19], v[172:175], v[192:195], v[16:19]
	v_mfma_f32_16x16x32_bf16 v[12:15], v[164:167], v[200:203], v[12:15]
	v_mfma_f32_16x16x32_bf16 v[8:11], v[172:175], v[200:203], v[8:11]
	v_mfma_f32_16x16x32_bf16 v[4:7], v[164:167], v[210:213], v[4:7]
	v_mfma_f32_16x16x32_bf16 v[0:3], v[172:175], v[210:213], v[0:3]
	v_mfma_f32_16x16x32_bf16 v[28:31], v[168:171], v[188:191], v[28:31]
	v_mfma_f32_16x16x32_bf16 v[24:27], v[180:183], v[188:191], v[24:27]
	v_mfma_f32_16x16x32_bf16 v[20:23], v[168:171], v[196:199], v[20:23]
	v_mfma_f32_16x16x32_bf16 v[16:19], v[180:183], v[196:199], v[16:19]
	v_mfma_f32_16x16x32_bf16 v[12:15], v[168:171], v[204:207], v[12:15]
	v_mfma_f32_16x16x32_bf16 v[8:11], v[180:183], v[204:207], v[8:11]
	v_mfma_f32_16x16x32_bf16 v[4:7], v[168:171], v[214:217], v[4:7]
	v_mfma_f32_16x16x32_bf16 v[0:3], v[180:183], v[214:217], v[0:3]
	s_setprio 0
	s_barrier
	v_add_u32_e32 v143, s70, v140
	ds_read_b128 v[144:147], v143
	ds_read_b128 v[148:151], v143 offset:1024
	ds_read_b128 v[152:155], v143 offset:2048
	ds_read_b128 v[156:159], v143 offset:3072
	v_add_u32_e32 v143, s69, v140
	ds_read_b128 v[164:167], v143
	ds_read_b128 v[168:171], v143 offset:1024
	ds_read_b128 v[172:175], v143 offset:2048
	ds_read_b128 v[180:183], v143 offset:3072
	s_mov_b32 m0, s61
	v_lshl_add_u64 v[222:223], s[46:47], 0, v[130:131]
	ds_read_b128 v[184:187], v142 offset:32768
	ds_read_b128 v[188:191], v142 offset:33792
	ds_read_b128 v[192:195], v142 offset:34816
	ds_read_b128 v[196:199], v142 offset:35840
	ds_read_b128 v[200:203], v142 offset:36864
	ds_read_b128 v[204:207], v142 offset:37888
	ds_read_b128 v[210:213], v142 offset:38912
	ds_read_b128 v[214:217], v142 offset:39936
	global_load_lds_dwordx4 v[222:223], off
	v_lshl_add_u64 v[222:223], s[46:47], 0, v[134:135]
	s_mov_b32 m0, s62
	s_nop 0
	global_load_lds_dwordx4 v[222:223], off
	s_waitcnt vmcnt(8)
	s_waitcnt lgkmcnt(0)
	s_barrier
	s_setprio 1
	s_waitcnt lgkmcnt(0)
	v_mfma_f32_16x16x32_bf16 v[124:127], v[144:147], v[184:187], v[124:127]
	v_mfma_f32_16x16x32_bf16 v[120:123], v[152:155], v[184:187], v[120:123]
	v_mfma_f32_16x16x32_bf16 v[116:119], v[144:147], v[192:195], v[116:119]
	v_mfma_f32_16x16x32_bf16 v[112:115], v[152:155], v[192:195], v[112:115]
	v_mfma_f32_16x16x32_bf16 v[108:111], v[144:147], v[200:203], v[108:111]
	v_mfma_f32_16x16x32_bf16 v[104:107], v[152:155], v[200:203], v[104:107]
	v_mfma_f32_16x16x32_bf16 v[100:103], v[144:147], v[210:213], v[100:103]
	v_mfma_f32_16x16x32_bf16 v[96:99], v[152:155], v[210:213], v[96:99]
	v_mfma_f32_16x16x32_bf16 v[124:127], v[148:151], v[188:191], v[124:127]
	v_mfma_f32_16x16x32_bf16 v[120:123], v[156:159], v[188:191], v[120:123]
	v_mfma_f32_16x16x32_bf16 v[116:119], v[148:151], v[196:199], v[116:119]
	v_mfma_f32_16x16x32_bf16 v[112:115], v[156:159], v[196:199], v[112:115]
	v_mfma_f32_16x16x32_bf16 v[108:111], v[148:151], v[204:207], v[108:111]
	v_mfma_f32_16x16x32_bf16 v[104:107], v[156:159], v[204:207], v[104:107]
	v_mfma_f32_16x16x32_bf16 v[100:103], v[148:151], v[214:217], v[100:103]
	v_mfma_f32_16x16x32_bf16 v[96:99], v[156:159], v[214:217], v[96:99]
	v_mfma_f32_16x16x32_bf16 v[92:95], v[164:167], v[184:187], v[92:95]
	v_mfma_f32_16x16x32_bf16 v[88:91], v[172:175], v[184:187], v[88:91]
	v_mfma_f32_16x16x32_bf16 v[84:87], v[164:167], v[192:195], v[84:87]
	v_mfma_f32_16x16x32_bf16 v[80:83], v[172:175], v[192:195], v[80:83]
	v_mfma_f32_16x16x32_bf16 v[76:79], v[164:167], v[200:203], v[76:79]
	v_mfma_f32_16x16x32_bf16 v[72:75], v[172:175], v[200:203], v[72:75]
	v_mfma_f32_16x16x32_bf16 v[68:71], v[164:167], v[210:213], v[68:71]
	v_mfma_f32_16x16x32_bf16 v[64:67], v[172:175], v[210:213], v[64:67]
	v_mfma_f32_16x16x32_bf16 v[92:95], v[168:171], v[188:191], v[92:95]
	v_mfma_f32_16x16x32_bf16 v[88:91], v[180:183], v[188:191], v[88:91]
	v_mfma_f32_16x16x32_bf16 v[84:87], v[168:171], v[196:199], v[84:87]
	v_mfma_f32_16x16x32_bf16 v[80:83], v[180:183], v[196:199], v[80:83]
	v_mfma_f32_16x16x32_bf16 v[76:79], v[168:171], v[204:207], v[76:79]
	v_mfma_f32_16x16x32_bf16 v[72:75], v[180:183], v[204:207], v[72:75]
	v_mfma_f32_16x16x32_bf16 v[68:71], v[168:171], v[214:217], v[68:71]
	v_mfma_f32_16x16x32_bf16 v[64:67], v[180:183], v[214:217], v[64:67]
	s_setprio 0
	s_barrier
	s_mov_b32 m0, s41
	v_lshl_add_u64 v[160:161], v[160:161], 0, s[20:21]
	ds_read_b128 v[184:187], v142 offset:49152
	ds_read_b128 v[188:191], v142 offset:50176
	ds_read_b128 v[192:195], v142 offset:51200
	ds_read_b128 v[196:199], v142 offset:52224
	ds_read_b128 v[200:203], v142 offset:53248
	ds_read_b128 v[204:207], v142 offset:54272
	ds_read_b128 v[210:213], v142 offset:55296
	ds_read_b128 v[214:217], v142 offset:56320
	global_load_lds_dwordx4 v[160:161], off
	v_lshl_add_u64 v[160:161], v[176:177], 0, s[20:21]
	s_mov_b32 m0, s29
	s_nop 0
	global_load_lds_dwordx4 v[160:161], off
	v_lshl_add_u64 v[160:161], s[44:45], 0, v[132:133]
	s_mov_b32 m0, s31
	s_nop 0
	global_load_lds_dwordx4 v[160:161], off
	v_lshl_add_u64 v[160:161], s[44:45], 0, v[136:137]
	s_mov_b32 m0, s27
	s_nop 0
	global_load_lds_dwordx4 v[160:161], off
	v_lshl_add_u64 v[160:161], v[218:219], 0, s[20:21]
	s_mov_b32 m0, s64
	s_nop 0
	global_load_lds_dwordx4 v[160:161], off
	v_lshl_add_u64 v[160:161], v[220:221], 0, s[20:21]
	s_mov_b32 m0, s65
	s_nop 0
	global_load_lds_dwordx4 v[160:161], off
	s_waitcnt vmcnt(8)
	s_waitcnt lgkmcnt(0)
	s_barrier
	s_setprio 1
	s_waitcnt lgkmcnt(0)
	v_mfma_f32_16x16x32_bf16 v[60:63], v[144:147], v[184:187], v[60:63]
	v_mfma_f32_16x16x32_bf16 v[56:59], v[152:155], v[184:187], v[56:59]
	v_mfma_f32_16x16x32_bf16 v[52:55], v[144:147], v[192:195], v[52:55]
	v_mfma_f32_16x16x32_bf16 v[48:51], v[152:155], v[192:195], v[48:51]
	v_mfma_f32_16x16x32_bf16 v[44:47], v[144:147], v[200:203], v[44:47]
	v_mfma_f32_16x16x32_bf16 v[40:43], v[152:155], v[200:203], v[40:43]
	v_mfma_f32_16x16x32_bf16 v[36:39], v[144:147], v[210:213], v[36:39]
	v_mfma_f32_16x16x32_bf16 v[32:35], v[152:155], v[210:213], v[32:35]
	v_mfma_f32_16x16x32_bf16 v[60:63], v[148:151], v[188:191], v[60:63]
	v_mfma_f32_16x16x32_bf16 v[56:59], v[156:159], v[188:191], v[56:59]
	v_mfma_f32_16x16x32_bf16 v[52:55], v[148:151], v[196:199], v[52:55]
	v_mfma_f32_16x16x32_bf16 v[48:51], v[156:159], v[196:199], v[48:51]
	v_mfma_f32_16x16x32_bf16 v[44:47], v[148:151], v[204:207], v[44:47]
	v_mfma_f32_16x16x32_bf16 v[40:43], v[156:159], v[204:207], v[40:43]
	v_mfma_f32_16x16x32_bf16 v[36:39], v[148:151], v[214:217], v[36:39]
	v_mfma_f32_16x16x32_bf16 v[32:35], v[156:159], v[214:217], v[32:35]
	v_mfma_f32_16x16x32_bf16 v[28:31], v[164:167], v[184:187], v[28:31]
	v_mfma_f32_16x16x32_bf16 v[24:27], v[172:175], v[184:187], v[24:27]
	v_mfma_f32_16x16x32_bf16 v[20:23], v[164:167], v[192:195], v[20:23]
	v_mfma_f32_16x16x32_bf16 v[16:19], v[172:175], v[192:195], v[16:19]
	v_mfma_f32_16x16x32_bf16 v[12:15], v[164:167], v[200:203], v[12:15]
	v_mfma_f32_16x16x32_bf16 v[8:11], v[172:175], v[200:203], v[8:11]
	v_mfma_f32_16x16x32_bf16 v[4:7], v[164:167], v[210:213], v[4:7]
	v_mfma_f32_16x16x32_bf16 v[0:3], v[172:175], v[210:213], v[0:3]
	v_mfma_f32_16x16x32_bf16 v[28:31], v[168:171], v[188:191], v[28:31]
	v_mfma_f32_16x16x32_bf16 v[24:27], v[180:183], v[188:191], v[24:27]
	v_mfma_f32_16x16x32_bf16 v[20:23], v[168:171], v[196:199], v[20:23]
	v_mfma_f32_16x16x32_bf16 v[16:19], v[180:183], v[196:199], v[16:19]
	v_mfma_f32_16x16x32_bf16 v[12:15], v[168:171], v[204:207], v[12:15]
	v_mfma_f32_16x16x32_bf16 v[8:11], v[180:183], v[204:207], v[8:11]
	v_mfma_f32_16x16x32_bf16 v[4:7], v[168:171], v[214:217], v[4:7]
	v_mfma_f32_16x16x32_bf16 v[0:3], v[180:183], v[214:217], v[0:3]
	s_setprio 0
	s_barrier
	s_add_i32 s101, s101, 0x100
	s_mov_b32 s27, s101
	s_cmp_eq_u32 s101, 0x300
	s_cselect_b64 s[44:45], -1, 0
	s_cmp_lg_u32 s101, 0x400
	s_cbranch_scc1 .LBB0_321
	s_and_b64 vcc, exec, s[22:23]
	s_cbranch_vccz .LBB0_324
	s_barrier

.LBB0_388:
	s_add_i32 s4, s7, s16
	s_mul_hi_i32 s7, s4, 0x88888889
	s_add_i32 s7, s7, s4
	s_lshr_b32 s16, s7, 31
	s_ashr_i32 s7, s7, 6
	s_add_i32 s7, s7, s16
	s_lshl_b32 s17, s7, 2
	s_sub_i32 s16, 35, s17
	s_min_i32 s41, s16, 4
	s_abs_i32 s42, s41
	v_cvt_f32_u32_e32 v0, s42
	s_sub_i32 s43, 0, s42
	s_mulk_i32 s7, 0x78
	s_sub_i32 s4, s4, s7
	v_rcp_iflag_f32_e32 v0, v0
	s_abs_i32 s16, s4
	s_xor_b32 s7, s4, s41
	s_ashr_i32 s7, s7, 31
	v_mul_f32_e32 v0, 0x4f7ffffe, v0
	v_cvt_u32_f32_e32 v0, v0
	s_nop 0
	v_readfirstlane_b32 s44, v0
	s_mul_i32 s43, s43, s44
	s_mul_hi_u32 s43, s44, s43
	s_add_i32 s44, s44, s43
	s_mul_hi_u32 s43, s16, s44
	s_mul_i32 s44, s43, s42
	s_sub_i32 s16, s16, s44
	s_add_i32 s44, s43, 1
	s_sub_i32 s45, s16, s42
	s_cmp_ge_u32 s16, s42
	s_cselect_b32 s43, s44, s43
	s_cselect_b32 s16, s45, s16
	s_add_i32 s44, s43, 1
	s_cmp_ge_u32 s16, s42
	s_cselect_b32 s16, s44, s43
	s_xor_b32 s16, s16, s7
	s_sub_i32 s16, s16, s7
	s_mul_i32 s7, s16, s41
	s_sub_i32 s4, s4, s7
	s_ashr_i32 s7, s6, 31
	s_lshl_b64 s[6:7], s[6:7], 20
	v_lshl_add_u64 v[0:1], v[16:17], 0, s[6:7]
	s_bfe_u32 s6, s40, 0x10002
	s_and_b32 s7, s40, 3
	s_add_i32 s17, s17, s4
	s_lshl_b32 s4, s6, 17
	s_lshl_b32 s41, s7, 14
	s_or_b32 s4, s4, s41
	v_lshl_add_u64 v[12:13], v[0:1], 0, s[4:5]
	global_load_dwordx4 v[52:55], v[12:13], off
	s_mov_b32 s4, 0x40000
	v_lshl_add_u64 v[198:199], v[12:13], 0, s[4:5]
	global_load_dwordx4 v[56:59], v[198:199], off
	s_mov_b32 s4, 0x80000
	v_lshl_add_u64 v[196:197], v[12:13], 0, s[4:5]
	global_load_dwordx4 v[60:63], v[196:197], off
	s_mov_b32 s4, 0xc0000
	v_lshl_add_u64 v[198:199], v[12:13], 0, s[4:5]
	global_load_dwordx4 v[64:67], v[198:199], off
	s_mov_b32 s4, 0x2000
	v_lshl_add_u64 v[196:197], v[12:13], 0, s[4:5]
	global_load_dwordx4 v[84:87], v[196:197], off
	s_mov_b32 s4, 0x42000
	v_lshl_add_u64 v[198:199], v[12:13], 0, s[4:5]
	global_load_dwordx4 v[88:91], v[198:199], off
	s_mov_b32 s4, 0x82000
	v_lshl_add_u64 v[196:197], v[12:13], 0, s[4:5]
	global_load_dwordx4 v[92:95], v[196:197], off
	s_mov_b32 s4, 0xc2000
	v_lshl_add_u64 v[198:199], v[12:13], 0, s[4:5]
	global_load_dwordx4 v[96:99], v[198:199], off
	s_mov_b32 s4, s3
	v_lshl_add_u64 v[196:197], v[12:13], 0, s[4:5]
	global_load_dwordx4 v[116:119], v[196:197], off
	s_mov_b32 s4, s18
	v_lshl_add_u64 v[198:199], v[12:13], 0, s[4:5]
	global_load_dwordx4 v[120:123], v[198:199], off
	s_mov_b32 s4, s19
	v_lshl_add_u64 v[196:197], v[12:13], 0, s[4:5]
	global_load_dwordx4 v[124:127], v[196:197], off
	s_mov_b32 s4, s20
	v_lshl_add_u64 v[198:199], v[12:13], 0, s[4:5]
	global_load_dwordx4 v[132:135], v[198:199], off
	s_mov_b32 s4, s25
	v_lshl_add_u64 v[196:197], v[12:13], 0, s[4:5]
	global_load_dwordx4 v[152:155], v[196:197], off
	s_mov_b32 s4, s26
	v_lshl_add_u64 v[198:199], v[12:13], 0, s[4:5]
	global_load_dwordx4 v[156:159], v[198:199], off
	s_mov_b32 s4, s27
	v_lshl_add_u64 v[196:197], v[12:13], 0, s[4:5]
	global_load_dwordx4 v[164:167], v[196:197], off
	s_mov_b32 s4, s28
	v_lshl_add_u64 v[198:199], v[12:13], 0, s[4:5]
	global_load_dwordx4 v[168:171], v[198:199], off
	s_or_b32 s7, s7, s2
	s_lshl_b32 s6, s6, 7
	s_lshl_b32 s7, s7, 4
	s_add_i32 s6, s7, s6
	s_waitcnt vmcnt(14)
	v_pk_add_f32 v[0:1], v[52:53], v[56:57]
	v_pk_add_f32 v[2:3], v[54:55], v[58:59]
	s_waitcnt vmcnt(13)
	v_pk_add_f32 v[0:1], v[0:1], v[60:61]
	v_pk_add_f32 v[2:3], v[2:3], v[62:63]
	s_waitcnt vmcnt(12)
	v_pk_add_f32 v[0:1], v[0:1], v[64:65]
	v_pk_add_f32 v[2:3], v[2:3], v[66:67]
	s_waitcnt vmcnt(12)
	s_waitcnt vmcnt(12)
	s_waitcnt vmcnt(12)
	s_waitcnt vmcnt(12)
	s_waitcnt vmcnt(10)
	v_pk_add_f32 v[4:5], v[84:85], v[88:89]
	v_pk_add_f32 v[6:7], v[86:87], v[90:91]
	s_waitcnt vmcnt(9)
	v_pk_add_f32 v[4:5], v[4:5], v[92:93]
	v_pk_add_f32 v[6:7], v[6:7], v[94:95]
	s_waitcnt vmcnt(8)
	v_pk_add_f32 v[4:5], v[4:5], v[96:97]
	v_pk_add_f32 v[6:7], v[6:7], v[98:99]
	s_waitcnt vmcnt(8)
	s_waitcnt vmcnt(8)
	s_waitcnt vmcnt(8)
	s_waitcnt vmcnt(8)
	s_waitcnt vmcnt(6)
	v_pk_add_f32 v[8:9], v[116:117], v[120:121]
	v_pk_add_f32 v[10:11], v[118:119], v[122:123]
	s_waitcnt vmcnt(5)
	v_pk_add_f32 v[8:9], v[8:9], v[124:125]
	v_pk_add_f32 v[10:11], v[10:11], v[126:127]
	s_waitcnt vmcnt(4)
	v_pk_add_f32 v[8:9], v[8:9], v[132:133]
	v_pk_add_f32 v[10:11], v[10:11], v[134:135]
	s_waitcnt vmcnt(4)
	s_waitcnt vmcnt(4)
	s_waitcnt vmcnt(4)
	s_waitcnt vmcnt(4)
	s_waitcnt vmcnt(2)
	v_pk_add_f32 v[12:13], v[152:153], v[156:157]
	v_pk_add_f32 v[14:15], v[154:155], v[158:159]
	s_waitcnt vmcnt(1)
	v_pk_add_f32 v[12:13], v[12:13], v[164:165]
	v_pk_add_f32 v[14:15], v[14:15], v[166:167]
	s_waitcnt vmcnt(0)
	v_pk_add_f32 v[12:13], v[12:13], v[168:169]
	v_pk_add_f32 v[14:15], v[14:15], v[170:171]
	s_waitcnt vmcnt(0)
	s_waitcnt vmcnt(0)
	s_waitcnt vmcnt(0)
	s_waitcnt vmcnt(0)
	s_lshl_b32 s4, s17, 8
	s_add_i32 s4, s6, s4
	s_mov_b64 s[6:7], -1
	s_cmp_gt_i32 s16, 13
	v_or_b32_e32 v20, s4, v162
	s_cbranch_scc1 .LBB0_390
	s_and_b64 vcc, exec, s[6:7]
	s_cbranch_vccz .LBB0_383
	s_branch .LBB0_401
